# adds conflict-free K-tile LDS swizzle and de-serialised attention epilogues on top of the barrier removal
# speedup vs baseline: 1.0230x; 1.0003x over previous
.LBB0_512:
	s_cmp_lt_i32 s70, 4
	s_cselect_b64 s[2:3], -1, 0
	s_and_b64 s[0:1], s[2:3], s[0:1]
	v_writelane_b32 v247, s0, 35
	s_andn2_b64 vcc, exec, s[0:1]
	s_nop 0
	v_writelane_b32 v247, s1, 36
	s_cbranch_vccnz .LBB0_602
	s_cmpk_gt_i32 s65, 0xff
	s_cbranch_scc1 .LBB0_602
	v_writelane_b32 v247, s94, 37
	v_lshlrev_b32_e32 v0, 4, v161
	v_and_b32_e32 v1, 0x3f0, v0
	v_writelane_b32 v247, s95, 38
	v_writelane_b32 v247, s86, 39
	s_add_i32 s0, 0, 0x1ec00
	v_lshrrev_b32_e32 v2, 1, v161
	v_writelane_b32 v247, s87, 40
	v_writelane_b32 v247, s80, 28
	v_add_u32_e32 v186, s0, v1
	v_lshrrev_b32_e32 v1, 2, v161
	v_writelane_b32 v247, s81, 29
	v_writelane_b32 v247, s78, 30
	v_and_b32_e32 v2, 8, v2
	v_lshrrev_b32_e32 v191, 3, v160
	v_writelane_b32 v247, s79, 31
	v_writelane_b32 v247, s76, 41
	v_writelane_b32 v247, s75, 32
	v_writelane_b32 v247, s74, 42
	v_writelane_b32 v247, s72, 43
	v_and_or_b32 v189, v1, 3, v2
	v_lshrrev_b32_e32 v1, 4, v161
	v_bitop3_b32 v1, v1, v161, 7 bitop3:0x28
	v_writelane_b32 v247, s73, 44
	v_writelane_b32 v247, s69, 45
	v_writelane_b32 v247, s70, 46
	v_lshlrev_b32_e32 v192, 4, v1
	v_lshlrev_b32_e32 v1, 3, v161
	v_writelane_b32 v247, s71, 47
	v_writelane_b32 v247, s84, 48
	v_lshlrev_b32_e32 v3, 1, v161
	s_cmp_lg_u32 0, -1
	v_writelane_b32 v247, s85, 49
	v_lshrrev_b32_e32 v185, 5, v160
	v_and_b32_e32 v2, 0xc0, v0
	v_and_b32_e32 v3, 32, v3
	v_and_b32_e32 v1, 0x118, v1
	s_cselect_b32 s1, 0, 0
	v_writelane_b32 v247, s86, 50
	v_and_b32_e32 v184, 31, v161
	v_or3_b32 v1, v3, v2, v1
	v_lshlrev_b32_e32 v3, 4, v185
	s_movk_i32 s0, 0x70
	s_add_i32 s2, s1, 0x4000
	v_writelane_b32 v247, s87, 51
	v_and_b32_e32 v190, 48, v0
	v_and_b32_e32 v2, 0xf0, v0
	v_lshlrev_b32_e32 v248, 3, v161
	v_and_b32_e32 v248, 0x70, v248
	v_lshl_add_u32 v4, v184, 8, s1
	v_lshl_add_u32 v5, v184, 7, s2
	v_xor_b32_e32 v0, v3, v2
	v_writelane_b32 v247, s88, 52
	v_add_u32_e32 v193, v0, v4
	v_xor_b32_e32 v253, v3, v248
	v_add_u32_e32 v194, v253, v5
	v_bitop3_b32 v0, v3, v2, 32 bitop3:0x36
	v_writelane_b32 v247, s89, 53
	v_add_u32_e32 v195, v0, v4
	v_bitop3_b32 v253, v3, v248, 32 bitop3:0x36
	v_add_u32_e32 v196, v253, v5
	v_bitop3_b32 v0, v3, v2, 64 bitop3:0x36
	s_movk_i32 s0, 0x60
	v_writelane_b32 v247, s90, 54
	v_add_u32_e32 v197, v0, v4
	v_bitop3_b32 v253, v3, v248, 64 bitop3:0x36
	v_add_u32_e32 v198, v253, v5
	v_bitop3_b32 v0, v3, v2, s0 bitop3:0x36
	v_writelane_b32 v247, s91, 55
	v_add_u32_e32 v199, v0, v4
	v_bitop3_b32 v253, v3, v248, s0 bitop3:0x36
	v_add_u32_e32 v200, v253, v5
	v_xor_b32_e32 v249, 0x80, v193
	v_xor_b32_e32 v250, 0x80, v195
	v_xor_b32_e32 v251, 0x80, v197
	v_xor_b32_e32 v252, 0x80, v199
	s_add_i32 s1, s1, 0x12000
	v_lshlrev_b32_e32 v0, 3, v185
	v_lshrrev_b32_e32 v187, 4, v160
	v_add_u32_e32 v202, s1, v1
	v_mov_b32_e32 v1, 0
	v_lshlrev_b32_e32 v2, 2, v185
	s_add_i32 s0, 0, 0x1e000
	v_lshlrev_b32_e32 v162, 1, v0
	v_writelane_b32 v247, s65, 56
	s_mov_b32 s87, 0
	v_and_b32_e32 v188, 15, v161
	v_or_b32_e32 v201, 0x100, v192
	v_add_u32_e32 v203, s0, v3
	v_lshl_or_b32 v204, v185, 6, v190
	v_sub_u32_e32 v205, v184, v2
	v_lshlrev_b32_e32 v206, 11, v187
	v_mov_b32_e32 v164, v162
	v_mov_b32_e32 v165, v1
	s_mov_b64 s[88:89], 0x30000
	v_lshlrev_b32_e32 v166, 1, v2
	v_mov_b32_e32 v167, v1
	s_mov_b32 s33, 0x41a00000
	v_lshlrev_b32_e32 v168, 2, v160
	v_mov_b32_e32 v207, 0xff800000
	v_writelane_b32 v247, s92, 57
	s_nop 1
	v_writelane_b32 v247, s93, 58
	s_branch .LBB0_516

.LBB0_518:
	s_and_b64 s[0:1], s[78:79], exec
	s_cselect_b32 s2, s82, s90
	s_cselect_b32 s3, s91, s83
	s_and_b64 s[0:1], s[98:99], exec
	s_cselect_b32 s1, s3, s2
	v_readfirstlane_b32 s3, v161
	s_lshr_b32 s2, s3, 6
	s_bfe_u32 s0, s3, 0x20006
	v_lshl_or_b32 v0, s0, 2, v187
	s_cmpk_lt_u32 s3, 0x100
	v_bitop3_b32 v2, v0, v188, 15 bitop3:0x6c
	v_mul_u32_u24_e32 v4, 0xc00, v0
	v_lshl_or_b32 v0, s0, 3, v191
	s_cselect_b64 s[80:81], -1, 0
	s_cmpk_gt_u32 s3, 0xff
	v_mul_u32_u24_e32 v6, 0xc00, v0
	s_cselect_b64 s[4:5], -1, 0
	v_lshlrev_b32_e32 v5, 4, v2
	v_or_b32_e32 v0, v5, v4
	s_and_b64 vcc, exec, s[4:5]
	v_add_u32_e32 v2, v6, v192
	s_cbranch_vccnz .LBB0_520
	s_lshl_b32 s0, s2, 10
	s_cmp_lg_u32 0, -1
	s_cselect_b32 s6, 0, 0
	s_add_i32 s0, s6, s0
	v_lshl_add_u64 v[8:9], s[76:77], 0, v[0:1]
	s_mov_b32 m0, s0
	s_mov_b64 s[6:7], 0xc000
	global_load_lds_dwordx4 v0, s[76:77]
	v_lshl_add_u64 v[10:11], v[8:9], 0, s[6:7]
	s_add_i32 m0, s0, 0x1000
	s_mov_b64 s[6:7], 0x18000
	global_load_lds_dwordx4 v[10:11], off
	v_lshl_add_u64 v[10:11], v[8:9], 0, s[6:7]
	s_add_i32 m0, s0, 0x2000
	s_mov_b64 s[6:7], 0x24000
	global_load_lds_dwordx4 v[10:11], off
	v_lshl_add_u64 v[8:9], v[8:9], 0, s[6:7]
	s_add_i32 m0, s0, 0x3000
	v_mov_b32_e32 v3, v1
	global_load_lds_dwordx4 v[8:9], off
	v_lshl_add_u64 v[8:9], s[76:77], 0, v[2:3]
	s_mov_b64 s[6:7], 0x100
	v_lshl_add_u64 v[10:11], v[8:9], 0, s[6:7]
	s_add_i32 m0, s0, 0x4000
	s_mov_b64 s[6:7], 0x18100
	global_load_lds_dwordx4 v[10:11], off
	v_lshl_add_u64 v[8:9], v[8:9], 0, s[6:7]
	s_add_i32 m0, s0, 0x5000
	s_nop 0
	global_load_lds_dwordx4 v[8:9], off

.LBB0_526:
	s_add_i32 s8, s97, s96
	s_add_i32 s7, s8, -2
	s_cmp_lt_i32 s7, 0
	s_cselect_b64 s[4:5], -1, 0
	s_cmp_le_i32 s95, s68
	s_cselect_b64 s[12:13], -1, 0
	s_or_b64 s[12:13], s[4:5], s[12:13]
	v_cndmask_b32_e64 v0, 0, 1, s[12:13]
	v_cmp_ne_u32_e64 s[4:5], 1, v0
	s_andn2_b64 vcc, exec, s[12:13]
	s_mov_b32 s72, s10
	s_cbranch_vccnz .LBB0_528
	s_mul_i32 s9, s72, 0x6000
	v_add_u32_e32 v0, s9, v193
	ds_read_b128 v[2:5], v0 offset:0
	ds_read_b128 v[6:9], v0 offset:0x2000
	v_add_u32_e32 v14, s9, v195
	ds_read_b128 v[10:13], v14 offset:0
	ds_read_b128 v[210:213], v14 offset:0x2000
	v_add_u32_e32 v15, s9, v197
	ds_read_b128 v[214:217], v15 offset:0
	s_waitcnt lgkmcnt(4)
	v_add_u32_e32 v209, s9, v199
	v_mfma_f32_32x32x16_bf16 v[80:95], v[2:5], v[112:115], 0
	ds_read_b128 v[2:5], v15 offset:0x2000
	s_waitcnt lgkmcnt(4)
	v_add_u32_e32 v253, s9, v249
	v_mfma_f32_32x32x16_bf16 v[96:111], v[6:9], v[112:115], 0
	ds_read_b128 v[6:9], v209 offset:0
	s_waitcnt lgkmcnt(4)
	v_add_u32_e32 v254, s9, v250
	v_mfma_f32_32x32x16_bf16 v[80:95], v[10:13], v[116:119], v[80:95]
	ds_read_b128 v[10:13], v209 offset:0x2000
	s_waitcnt lgkmcnt(4)
	v_add_u32_e32 v255, s9, v251
	v_mfma_f32_32x32x16_bf16 v[96:111], v[210:213], v[116:119], v[96:111]
	ds_read_b128 v[210:213], v253 offset:0
	s_waitcnt lgkmcnt(4)
	v_add_u32_e32 v248, s9, v252
	v_mfma_f32_32x32x16_bf16 v[80:95], v[214:217], v[120:123], v[80:95]
	ds_read_b128 v[214:217], v253 offset:0x2000
	s_waitcnt lgkmcnt(4)
	v_add_u32_e32 v0, s9, v194
	v_mfma_f32_32x32x16_bf16 v[96:111], v[2:5], v[120:123], v[96:111]
	ds_read_b128 v[2:5], v254 offset:0
	s_waitcnt lgkmcnt(4)
	s_nop 0
	v_mfma_f32_32x32x16_bf16 v[80:95], v[6:9], v[124:127], v[80:95]
	ds_read_b128 v[6:9], v254 offset:0x2000
	s_waitcnt lgkmcnt(4)
	s_nop 0
	v_mfma_f32_32x32x16_bf16 v[96:111], v[10:13], v[124:127], v[96:111]
	ds_read_b128 v[10:13], v255 offset:0
	s_waitcnt lgkmcnt(4)
	s_nop 0
	v_mfma_f32_32x32x16_bf16 v[80:95], v[210:213], v[128:131], v[80:95]
	ds_read_b128 v[210:213], v255 offset:0x2000
	s_waitcnt lgkmcnt(4)
	s_nop 0
	v_mfma_f32_32x32x16_bf16 v[96:111], v[214:217], v[128:131], v[96:111]
	ds_read_b128 v[214:217], v248 offset:0
	s_waitcnt lgkmcnt(4)
	s_nop 0
	v_mfma_f32_32x32x16_bf16 v[80:95], v[2:5], v[132:135], v[80:95]
	ds_read_b128 v[2:5], v248 offset:0x2000
	s_waitcnt lgkmcnt(4)
	s_nop 0
	v_mfma_f32_32x32x16_bf16 v[96:111], v[6:9], v[132:135], v[96:111]
	ds_read_b128 v[6:9], v0 offset:0
	ds_read_b128 v[218:221], v169 offset:0
	s_waitcnt lgkmcnt(5)
	s_nop 0
	v_mfma_f32_32x32x16_bf16 v[80:95], v[10:13], v[136:139], v[80:95]
	ds_read_b128 v[10:13], v0 offset:0x1000
	s_waitcnt lgkmcnt(5)
	v_add_u32_e32 v0, s9, v196
	v_mfma_f32_32x32x16_bf16 v[96:111], v[210:213], v[136:139], v[96:111]
	ds_read_b128 v[210:213], v0 offset:0
	ds_read_b128 v[222:225], v169 offset:0x400
	s_waitcnt lgkmcnt(6)
	s_nop 0
	v_mfma_f32_32x32x16_bf16 v[80:95], v[214:217], v[140:143], v[80:95]
	ds_read_b128 v[214:217], v0 offset:0x1000
	s_waitcnt lgkmcnt(6)
	v_add_u32_e32 v0, s9, v198
	v_mfma_f32_32x32x16_bf16 v[96:111], v[2:5], v[140:143], v[96:111]
	ds_read_b128 v[2:5], v0 offset:0
	ds_read_b128 v[226:229], v169 offset:0x800
	s_waitcnt lgkmcnt(6)
	s_nop 0
	v_mfma_f32_32x32x16_bf16 v[80:95], v[6:9], v[218:221], v[80:95]
	ds_read_b128 v[6:9], v0 offset:0x1000
	s_waitcnt lgkmcnt(6)
	v_add_u32_e32 v0, s9, v200
	v_mfma_f32_32x32x16_bf16 v[96:111], v[10:13], v[218:221], v[96:111]
	ds_read_b128 v[10:13], v0 offset:0
	ds_read_b128 v[218:221], v169 offset:0xc00
	s_waitcnt lgkmcnt(6)
	s_nop 0
	v_mfma_f32_32x32x16_bf16 v[80:95], v[210:213], v[222:225], v[80:95]
	ds_read_b128 v[210:213], v0 offset:0x1000
	s_waitcnt lgkmcnt(6)
	s_waitcnt lgkmcnt(4)
	s_nop 0
	v_mfma_f32_32x32x16_bf16 v[96:111], v[214:217], v[222:225], v[96:111]
	v_mfma_f32_32x32x16_bf16 v[80:95], v[2:5], v[226:229], v[80:95]
	s_waitcnt lgkmcnt(3)
	s_waitcnt lgkmcnt(1)
	s_nop 0
	v_mfma_f32_32x32x16_bf16 v[96:111], v[6:9], v[226:229], v[96:111]
	v_mfma_f32_32x32x16_bf16 v[80:95], v[10:13], v[218:221], v[80:95]
	s_waitcnt lgkmcnt(0)
	s_nop 0
	v_mfma_f32_32x32x16_bf16 v[96:111], v[210:213], v[218:221], v[96:111]

.LBB0_561:
	s_and_b64 s[0:1], s[84:85], exec
	s_cselect_b32 s2, s91, s83
	s_cselect_b32 s3, s82, s90
	s_and_b64 s[0:1], s[98:99], exec
	v_readfirstlane_b32 s80, v161
	s_cselect_b32 s0, s3, s2
	s_lshr_b32 s1, s80, 6
	s_cmpk_lt_u32 s80, 0x100
	s_cselect_b64 s[70:71], -1, 0
	s_cmpk_gt_u32 s80, 0xff
	s_cselect_b64 s[4:5], -1, 0
	s_lshr_b32 s2, s80, 4
	v_and_or_b32 v0, s2, 12, v187
	v_bitop3_b32 v2, v0, v188, 15 bitop3:0x6c
	v_lshlrev_b32_e32 v2, 4, v2
	v_lshl_or_b32 v0, v0, 11, v2
	s_and_b64 vcc, exec, s[4:5]
	s_cbranch_vccnz .LBB0_563
	s_lshl_b32 s2, s1, 10
	s_cmp_lg_u32 0, -1
	s_cselect_b32 s3, 0, 0
	s_add_i32 s2, s3, s2
	v_lshl_add_u64 v[4:5], s[74:75], 0, v[0:1]
	s_mov_b32 m0, s2
	s_mov_b64 s[6:7], 0x8000
	global_load_lds_dwordx4 v0, s[74:75]
	v_lshl_add_u64 v[6:7], v[4:5], 0, s[6:7]
	s_add_i32 m0, s2, 0x1000
	s_mov_b64 s[6:7], 0x10000
	global_load_lds_dwordx4 v[6:7], off
	v_lshl_add_u64 v[6:7], v[4:5], 0, s[6:7]
	s_add_i32 m0, s2, 0x2000
	s_mov_b64 s[6:7], 0x18000
	global_load_lds_dwordx4 v[6:7], off
	v_lshl_add_u64 v[4:5], v[4:5], 0, s[6:7]
	s_add_i32 m0, s2, 0x3000
	s_nop 0
	global_load_lds_dwordx4 v[4:5], off
	s_add_i32 m0, s3, 0x1e000
	s_nop 0
	global_load_lds_dword v[146:147], off

.LBB0_573:
	s_add_i32 s7, s69, s0
	s_cmp_lt_i32 s7, 0
	s_cselect_b64 s[4:5], -1, 0
	s_add_i32 s8, s68, s86
	s_add_i32 s9, s8, 0xffffff80
	s_cmp_le_i32 s9, s95
	s_cselect_b64 s[10:11], -1, 0
	s_or_b64 s[10:11], s[4:5], s[10:11]
	v_cndmask_b32_e64 v2, 0, 1, s[10:11]
	v_cmp_ne_u32_e64 s[4:5], 1, v2
	s_andn2_b64 vcc, exec, s[10:11]
	s_cbranch_vccnz .LBB0_575
	s_mul_i32 s9, s1, 0x6000
	v_add_u32_e32 v14, s9, v193
	ds_read_b128 v[2:5], v14 offset:0
	ds_read_b128 v[6:9], v14 offset:0x2000
	v_add_u32_e32 v15, s9, v195
	ds_read_b128 v[10:13], v15 offset:0
	ds_read_b128 v[174:177], v15 offset:0x2000
	v_add_u32_e32 v159, s9, v197
	ds_read_b128 v[178:181], v159 offset:0
	s_waitcnt lgkmcnt(4)
	v_add_u32_e32 v163, s9, v199
	v_mfma_f32_32x32x16_bf16 v[96:111], v[2:5], v[112:115], 0
	ds_read_b128 v[2:5], v159 offset:0x2000
	s_waitcnt lgkmcnt(4)
	v_add_u32_e32 v253, s9, v249
	v_mfma_f32_32x32x16_bf16 v[80:95], v[6:9], v[112:115], 0
	ds_read_b128 v[6:9], v163 offset:0
	s_waitcnt lgkmcnt(4)
	v_add_u32_e32 v254, s9, v250
	v_mfma_f32_32x32x16_bf16 v[96:111], v[10:13], v[116:119], v[96:111]
	ds_read_b128 v[10:13], v163 offset:0x2000
	s_waitcnt lgkmcnt(4)
	v_add_u32_e32 v255, s9, v251
	v_mfma_f32_32x32x16_bf16 v[80:95], v[174:177], v[116:119], v[80:95]
	ds_read_b128 v[174:177], v253 offset:0
	ds_read_b128 v[208:211], v156 offset:0
	s_waitcnt lgkmcnt(5)
	v_add_u32_e32 v248, s9, v252
	v_mfma_f32_32x32x16_bf16 v[96:111], v[178:181], v[120:123], v[96:111]
	ds_read_b128 v[178:181], v253 offset:0x2000
	s_waitcnt lgkmcnt(5)
	s_nop 0
	v_mfma_f32_32x32x16_bf16 v[80:95], v[2:5], v[120:123], v[80:95]
	ds_read_b128 v[2:5], v254 offset:0
	ds_read_b128 v[212:215], v156 offset:0x400
	s_waitcnt lgkmcnt(6)
	s_nop 0
	v_mfma_f32_32x32x16_bf16 v[96:111], v[6:9], v[124:127], v[96:111]
	ds_read_b128 v[6:9], v254 offset:0x2000
	s_waitcnt lgkmcnt(6)
	s_nop 0
	v_mfma_f32_32x32x16_bf16 v[80:95], v[10:13], v[124:127], v[80:95]
	ds_read_b128 v[10:13], v255 offset:0
	ds_read_b128 v[216:219], v156 offset:0x800
	s_waitcnt lgkmcnt(6)
	s_nop 0
	v_mfma_f32_32x32x16_bf16 v[96:111], v[174:177], v[208:211], v[96:111]
	ds_read_b128 v[174:177], v255 offset:0x2000
	s_waitcnt lgkmcnt(6)
	s_nop 0
	v_mfma_f32_32x32x16_bf16 v[80:95], v[178:181], v[208:211], v[80:95]
	ds_read_b128 v[178:181], v248 offset:0
	ds_read_b128 v[208:211], v156 offset:0xc00
	s_waitcnt lgkmcnt(6)
	s_nop 0
	v_mfma_f32_32x32x16_bf16 v[96:111], v[2:5], v[212:215], v[96:111]
	ds_read_b128 v[2:5], v248 offset:0x2000
	s_waitcnt lgkmcnt(6)
	s_waitcnt lgkmcnt(4)
	s_nop 0
	v_mfma_f32_32x32x16_bf16 v[80:95], v[6:9], v[212:215], v[80:95]
	v_mfma_f32_32x32x16_bf16 v[96:111], v[10:13], v[216:219], v[96:111]
	s_waitcnt lgkmcnt(3)
	s_waitcnt lgkmcnt(1)
	s_nop 0
	v_mfma_f32_32x32x16_bf16 v[80:95], v[174:177], v[216:219], v[80:95]
	v_mfma_f32_32x32x16_bf16 v[96:111], v[178:181], v[208:211], v[96:111]
	s_waitcnt lgkmcnt(0)
	s_nop 0
	v_mfma_f32_32x32x16_bf16 v[80:95], v[2:5], v[208:211], v[80:95]

	.amdhsa_kernel _Z10hybrid_fwd4Args
		.amdhsa_group_segment_fixed_size 0
		.amdhsa_private_segment_fixed_size 0
		.amdhsa_kernarg_size 368
		.amdhsa_user_sgpr_count 2
		.amdhsa_user_sgpr_dispatch_ptr 0
		.amdhsa_user_sgpr_queue_ptr 0
		.amdhsa_user_sgpr_kernarg_segment_ptr 1
		.amdhsa_user_sgpr_dispatch_id 0
		.amdhsa_user_sgpr_kernarg_preload_length 0
		.amdhsa_user_sgpr_kernarg_preload_offset 0
		.amdhsa_user_sgpr_private_segment_size 0
		.amdhsa_uses_dynamic_stack 0
		.amdhsa_enable_private_segment 0
		.amdhsa_system_sgpr_workgroup_id_x 1
		.amdhsa_system_sgpr_workgroup_id_y 0
		.amdhsa_system_sgpr_workgroup_id_z 0
		.amdhsa_system_sgpr_workgroup_info 0
		.amdhsa_system_vgpr_workitem_id 2
		.amdhsa_next_free_vgpr 256
		.amdhsa_next_free_sgpr 102
		.amdhsa_accum_offset 256
		.amdhsa_reserve_vcc 1
		.amdhsa_float_round_mode_32 0
		.amdhsa_float_round_mode_16_64 0
		.amdhsa_float_denorm_mode_32 3
		.amdhsa_float_denorm_mode_16_64 3
		.amdhsa_dx10_clamp 1
		.amdhsa_ieee_mode 1
		.amdhsa_fp16_overflow 0
		.amdhsa_tg_split 0
		.amdhsa_exception_fp_ieee_invalid_op 0
		.amdhsa_exception_fp_denorm_src 0
		.amdhsa_exception_fp_ieee_div_zero 0
		.amdhsa_exception_fp_ieee_overflow 0
		.amdhsa_exception_fp_ieee_underflow 0
		.amdhsa_exception_fp_ieee_inexact 0
		.amdhsa_exception_int_div_zero 0
	.end_amdhsa_kernel

amdhsa.kernels:
  - .agpr_count:     0
    .args:
      - .offset:         0
        .size:           112
        .value_kind:     by_value
      - .offset:         112
        .size:           4
        .value_kind:     hidden_block_count_x
      - .offset:         116
        .size:           4
        .value_kind:     hidden_block_count_y
      - .offset:         120
        .size:           4
        .value_kind:     hidden_block_count_z
      - .offset:         124
        .size:           2
        .value_kind:     hidden_group_size_x
      - .offset:         126
        .size:           2
        .value_kind:     hidden_group_size_y
      - .offset:         128
        .size:           2
        .value_kind:     hidden_group_size_z
      - .offset:         130
        .size:           2
        .value_kind:     hidden_remainder_x
      - .offset:         132
        .size:           2
        .value_kind:     hidden_remainder_y
      - .offset:         134
        .size:           2
        .value_kind:     hidden_remainder_z
      - .offset:         152
        .size:           8
        .value_kind:     hidden_global_offset_x
      - .offset:         160
        .size:           8
        .value_kind:     hidden_global_offset_y
      - .offset:         168
        .size:           8
        .value_kind:     hidden_global_offset_z
      - .offset:         176
        .size:           2
        .value_kind:     hidden_grid_dims
      - .offset:         200
        .size:           8
        .value_kind:     hidden_multigrid_sync_arg
      - .offset:         232
        .size:           4
        .value_kind:     hidden_dynamic_lds_size
    .group_segment_fixed_size: 0
    .kernarg_segment_align: 8
    .kernarg_segment_size: 368
    .language:       OpenCL C
    .language_version:
      - 2
      - 0
    .max_flat_workgroup_size: 512
    .name:           _Z10hybrid_fwd4Args
    .private_segment_fixed_size: 0
    .sgpr_count:     108
    .sgpr_spill_count: 72
    .symbol:         _Z10hybrid_fwd4Args.kd
    .uniform_work_group_size: 1
    .uses_dynamic_stack: false
    .vgpr_count:     256
    .vgpr_spill_count: 0
    .wavefront_size: 64
